# P0 compress-bias partial sums loop software-pipelined (two register sets, FMA order unchanged)
# speedup vs baseline: 1.0051x; 1.0051x over previous
.LBB0_150:
	v_lshlrev_b32_e32 v1, 13, v6
	v_and_b32_e32 v2, 0x200000, v1
	v_lshlrev_b32_e32 v1, 5, v6
	v_and_b32_e32 v10, 0x2000, v1
	v_ashrrev_i32_e32 v1, 2, v6
	v_and_b32_e32 v12, 0xffffff80, v1
	v_ashrrev_i32_e32 v13, 31, v12
	v_mov_b32_e32 v11, v3
	v_lshlrev_b64 v[8:9], 10, v[12:13]
	v_lshl_add_u64 v[8:9], v[2:3], 0, v[8:9]
	v_lshl_add_u64 v[10:11], v[12:13], 2, v[10:11]
	v_lshl_add_u64 v[8:9], v[4:5], 0, v[8:9]
	v_lshl_add_u64 v[10:11], s[4:5], 0, v[10:11]
	s_mov_b64 s[20:21], 0
	v_mov_b32_e32 v1, 0
	s_mov_b32 s48, 0xffffc400
	s_mov_b32 s49, -1
	s_mov_b32 s50, 0xffffd400
	s_mov_b32 s51, -1
	s_mov_b32 s56, 0xffffe400
	s_mov_b32 s57, -1
	s_mov_b32 s58, 0xfffff400
	s_mov_b32 s59, -1
	v_lshl_add_u64 v[108:109], v[10:11], 0, s[20:21]
	global_load_dwordx4 v[44:47], v[108:109], off
	global_load_dwordx4 v[48:51], v[108:109], off offset:16
	global_load_dwordx4 v[52:55], v[108:109], off offset:32
	global_load_dwordx4 v[56:59], v[108:109], off offset:48
	s_add_u32 s20, s20, 64
	s_addc_u32 s21, s21, 0
	v_lshl_add_u64 v[110:111], v[8:9], 0, s[48:49]
	global_load_dword v60, v[110:111], off
	global_load_dword v61, v[110:111], off offset:1024
	global_load_dword v62, v[110:111], off offset:2048
	global_load_dword v63, v[110:111], off offset:3072
	v_lshl_add_u64 v[108:109], v[8:9], 0, s[50:51]
	global_load_dword v64, v[108:109], off
	global_load_dword v65, v[108:109], off offset:1024
	global_load_dword v66, v[108:109], off offset:2048
	global_load_dword v67, v[108:109], off offset:3072
	v_lshl_add_u64 v[110:111], v[8:9], 0, s[56:57]
	global_load_dword v68, v[110:111], off
	global_load_dword v69, v[110:111], off offset:1024
	global_load_dword v70, v[110:111], off offset:2048
	global_load_dword v71, v[110:111], off offset:3072
	v_lshl_add_u64 v[108:109], v[8:9], 0, s[58:59]
	global_load_dword v72, v[108:109], off
	global_load_dword v73, v[108:109], off offset:1024
	global_load_dword v74, v[108:109], off offset:2048
	global_load_dword v75, v[108:109], off offset:3072
	v_lshl_add_u64 v[8:9], v[8:9], 0, s[6:7]
	s_mov_b32 s60, 0
.Lb1_loop:
	v_lshl_add_u64 v[108:109], v[10:11], 0, s[20:21]
	global_load_dwordx4 v[76:79], v[108:109], off
	global_load_dwordx4 v[80:83], v[108:109], off offset:16
	global_load_dwordx4 v[84:87], v[108:109], off offset:32
	global_load_dwordx4 v[88:91], v[108:109], off offset:48
	s_add_u32 s20, s20, 64
	s_addc_u32 s21, s21, 0
	v_lshl_add_u64 v[110:111], v[8:9], 0, s[48:49]
	global_load_dword v92, v[110:111], off
	global_load_dword v93, v[110:111], off offset:1024
	global_load_dword v94, v[110:111], off offset:2048
	global_load_dword v95, v[110:111], off offset:3072
	v_lshl_add_u64 v[108:109], v[8:9], 0, s[50:51]
	global_load_dword v96, v[108:109], off
	global_load_dword v97, v[108:109], off offset:1024
	global_load_dword v98, v[108:109], off offset:2048
	global_load_dword v99, v[108:109], off offset:3072
	v_lshl_add_u64 v[110:111], v[8:9], 0, s[56:57]
	global_load_dword v100, v[110:111], off
	global_load_dword v101, v[110:111], off offset:1024
	global_load_dword v102, v[110:111], off offset:2048
	global_load_dword v103, v[110:111], off offset:3072
	v_lshl_add_u64 v[108:109], v[8:9], 0, s[58:59]
	global_load_dword v104, v[108:109], off
	global_load_dword v105, v[108:109], off offset:1024
	global_load_dword v106, v[108:109], off offset:2048
	global_load_dword v107, v[108:109], off offset:3072
	v_lshl_add_u64 v[8:9], v[8:9], 0, s[6:7]
	s_waitcnt vmcnt(35)
	v_fmac_f32_e32 v1, v44, v60
	s_waitcnt vmcnt(34)
	v_fmac_f32_e32 v1, v45, v61
	s_waitcnt vmcnt(33)
	v_fmac_f32_e32 v1, v46, v62
	s_waitcnt vmcnt(32)
	v_fmac_f32_e32 v1, v47, v63
	s_waitcnt vmcnt(31)
	v_fmac_f32_e32 v1, v48, v64
	s_waitcnt vmcnt(30)
	v_fmac_f32_e32 v1, v49, v65
	s_waitcnt vmcnt(29)
	v_fmac_f32_e32 v1, v50, v66
	s_waitcnt vmcnt(28)
	v_fmac_f32_e32 v1, v51, v67
	s_waitcnt vmcnt(27)
	v_fmac_f32_e32 v1, v52, v68
	s_waitcnt vmcnt(26)
	v_fmac_f32_e32 v1, v53, v69
	s_waitcnt vmcnt(25)
	v_fmac_f32_e32 v1, v54, v70
	s_waitcnt vmcnt(24)
	v_fmac_f32_e32 v1, v55, v71
	s_waitcnt vmcnt(23)
	v_fmac_f32_e32 v1, v56, v72
	s_waitcnt vmcnt(22)
	v_fmac_f32_e32 v1, v57, v73
	s_waitcnt vmcnt(21)
	v_fmac_f32_e32 v1, v58, v74
	s_waitcnt vmcnt(20)
	v_fmac_f32_e32 v1, v59, v75
	s_cmp_eq_u32 s60, 3
	s_cbranch_scc1 .Lb1_last
	v_lshl_add_u64 v[108:109], v[10:11], 0, s[20:21]
	global_load_dwordx4 v[44:47], v[108:109], off
	global_load_dwordx4 v[48:51], v[108:109], off offset:16
	global_load_dwordx4 v[52:55], v[108:109], off offset:32
	global_load_dwordx4 v[56:59], v[108:109], off offset:48
	s_add_u32 s20, s20, 64
	s_addc_u32 s21, s21, 0
	v_lshl_add_u64 v[110:111], v[8:9], 0, s[48:49]
	global_load_dword v60, v[110:111], off
	global_load_dword v61, v[110:111], off offset:1024
	global_load_dword v62, v[110:111], off offset:2048
	global_load_dword v63, v[110:111], off offset:3072
	v_lshl_add_u64 v[108:109], v[8:9], 0, s[50:51]
	global_load_dword v64, v[108:109], off
	global_load_dword v65, v[108:109], off offset:1024
	global_load_dword v66, v[108:109], off offset:2048
	global_load_dword v67, v[108:109], off offset:3072
	v_lshl_add_u64 v[110:111], v[8:9], 0, s[56:57]
	global_load_dword v68, v[110:111], off
	global_load_dword v69, v[110:111], off offset:1024
	global_load_dword v70, v[110:111], off offset:2048
	global_load_dword v71, v[110:111], off offset:3072
	v_lshl_add_u64 v[108:109], v[8:9], 0, s[58:59]
	global_load_dword v72, v[108:109], off
	global_load_dword v73, v[108:109], off offset:1024
	global_load_dword v74, v[108:109], off offset:2048
	global_load_dword v75, v[108:109], off offset:3072
	v_lshl_add_u64 v[8:9], v[8:9], 0, s[6:7]
	s_waitcnt vmcnt(35)
	v_fmac_f32_e32 v1, v76, v92
	s_waitcnt vmcnt(34)
	v_fmac_f32_e32 v1, v77, v93
	s_waitcnt vmcnt(33)
	v_fmac_f32_e32 v1, v78, v94
	s_waitcnt vmcnt(32)
	v_fmac_f32_e32 v1, v79, v95
	s_waitcnt vmcnt(31)
	v_fmac_f32_e32 v1, v80, v96
	s_waitcnt vmcnt(30)
	v_fmac_f32_e32 v1, v81, v97
	s_waitcnt vmcnt(29)
	v_fmac_f32_e32 v1, v82, v98
	s_waitcnt vmcnt(28)
	v_fmac_f32_e32 v1, v83, v99
	s_waitcnt vmcnt(27)
	v_fmac_f32_e32 v1, v84, v100
	s_waitcnt vmcnt(26)
	v_fmac_f32_e32 v1, v85, v101
	s_waitcnt vmcnt(25)
	v_fmac_f32_e32 v1, v86, v102
	s_waitcnt vmcnt(24)
	v_fmac_f32_e32 v1, v87, v103
	s_waitcnt vmcnt(23)
	v_fmac_f32_e32 v1, v88, v104
	s_waitcnt vmcnt(22)
	v_fmac_f32_e32 v1, v89, v105
	s_waitcnt vmcnt(21)
	v_fmac_f32_e32 v1, v90, v106
	s_waitcnt vmcnt(20)
	v_fmac_f32_e32 v1, v91, v107
	s_add_u32 s60, s60, 1
	s_branch .Lb1_loop
.Lb1_last:
	s_waitcnt vmcnt(15)
	v_fmac_f32_e32 v1, v76, v92
	s_waitcnt vmcnt(14)
	v_fmac_f32_e32 v1, v77, v93
	s_waitcnt vmcnt(13)
	v_fmac_f32_e32 v1, v78, v94
	s_waitcnt vmcnt(12)
	v_fmac_f32_e32 v1, v79, v95
	s_waitcnt vmcnt(11)
	v_fmac_f32_e32 v1, v80, v96
	s_waitcnt vmcnt(10)
	v_fmac_f32_e32 v1, v81, v97
	s_waitcnt vmcnt(9)
	v_fmac_f32_e32 v1, v82, v98
	s_waitcnt vmcnt(8)
	v_fmac_f32_e32 v1, v83, v99
	s_waitcnt vmcnt(7)
	v_fmac_f32_e32 v1, v84, v100
	s_waitcnt vmcnt(6)
	v_fmac_f32_e32 v1, v85, v101
	s_waitcnt vmcnt(5)
	v_fmac_f32_e32 v1, v86, v102
	s_waitcnt vmcnt(4)
	v_fmac_f32_e32 v1, v87, v103
	s_waitcnt vmcnt(3)
	v_fmac_f32_e32 v1, v88, v104
	s_waitcnt vmcnt(2)
	v_fmac_f32_e32 v1, v89, v105
	s_waitcnt vmcnt(1)
	v_fmac_f32_e32 v1, v90, v106
	s_waitcnt vmcnt(0)
	v_fmac_f32_e32 v1, v91, v107
	v_ashrrev_i32_e32 v7, 31, v6
	v_lshl_add_u64 v[8:9], v[6:7], 2, s[8:9]
	v_add_u32_e32 v6, s16, v6
	v_cmp_lt_i32_e32 vcc, s24, v6
	s_or_b64 s[0:1], vcc, s[0:1]
	global_store_dword v[8:9], v1, off
	s_andn2_b64 exec, exec, s[0:1]
	s_cbranch_execnz .LBB0_150
